# attention QK sections: K fragments double-buffered (second register set v[234:241]); each fragment pair is read one pair earlier, so its LDS latency runs under the previous pair's MFMAs
# speedup vs baseline: 1.0129x; 1.0129x over previous
; __device__ __forceinline__ void finishSM(f32x16& p0, f32x16& p1, float alpha, float& l_reg, bf16x8& pa0, bf16x8& pa1, bf16x8& pa2, bf16x8& pa3) {
;     for (int r = 0; r < 16; ++r) p1[r] = __builtin_amdgcn_exp2f(p1[r]);
;     float ps = 0; for (int r = 0; r < 16; ++r) ps += p0[r]; for (int r = 0; r < 16; ++r) ps += p1[r];
;     { auto rr = __builtin_amdgcn_permlane32_swap(__float_as_uint(ps), __float_as_uint(ps), false, false);
;       ps = __uint_as_float(rr[0]) + __uint_as_float(rr[1]); }
;     l_reg = l_reg * alpha + ps;
;     ...
;     PK4(p0, 0, pa0); PK4(p0, 8, pa1); PK4(p1, 0, pa2); PK4(p1, 8, pa3);
;     ...
; }
; template <int KB>
; __device__ __forceinline__ void qkt(f32x16& p0, f32x16& p1, const char* K_lds, int r32, int hi, const bf16x8* qr) {
;     p0 = f32x16{}; p1 = f32x16{};
;     const char* kb[4];
; #pragma unroll
;     for (int dd = 0; dd < 4; ++dd) kb[dd] = K_lds + KB * SHM_K + KSWZ(r32, (dd * 16 + hi * 8) * 2);
; #pragma unroll
;     for (int d0 = 0; d0 < 8; ++d0) { const char* a = kb[d0 & 3] + (d0 >> 2) * 128;
;         bf16x8 b0 = *reinterpret_cast<const bf16x8*>(a);
;         bf16x8 b1 = *reinterpret_cast<const bf16x8*>(a + 32 * 256);
;         p0 = __builtin_amdgcn_mfma_f32_32x32x16_bf16(b0, qr[d0], p0, 0, 0, 0);
;         p1 = __builtin_amdgcn_mfma_f32_32x32x16_bf16(b1, qr[d0], p1, 0, 0, 0); }
; }
.LBB0_89:
	ds_read_b128 v[66:69], v169 offset:49152
	ds_read_b128 v[70:73], v169 offset:57344
	ds_read_b128 v[100:103], v193 offset:49152
	ds_read_b128 v[136:139], v193 offset:57344
	ds_read_b128 v[234:237], v194 offset:49152
	ds_read_b128 v[238:241], v194 offset:57344
	v_add_f32_e32 v148, 0, v231
	v_add_f32_e32 v148, v233, v148
	v_add_f32_e32 v148, v229, v148
	v_add_f32_e32 v148, v232, v148
	v_add_f32_e32 v148, v228, v148
	v_add_f32_e32 v148, v230, v148
	v_add_f32_e32 v148, v226, v148
	v_add_f32_e32 v148, v227, v148
	v_add_f32_e32 v148, v223, v148
	v_add_f32_e32 v148, v225, v148
	v_add_f32_e32 v148, v209, v148
	v_add_f32_e32 v148, v224, v148
	v_add_f32_e32 v148, v206, v148
	v_add_f32_e32 v148, v208, v148
	v_add_f32_e32 v148, v205, v148
	v_add_f32_e32 v148, v207, v148
	v_exp_f32_e32 v140, v152
	v_exp_f32_e32 v141, v153
	v_exp_f32_e32 v142, v180
	v_exp_f32_e32 v143, v181
	s_waitcnt lgkmcnt(5)
	v_mfma_f32_32x32x16_bf16 v[82:97], v[66:69], v[132:135], 0
	v_exp_f32_e32 v144, v160
	v_exp_f32_e32 v145, v161
	v_exp_f32_e32 v146, v154
	v_exp_f32_e32 v147, v155
	s_waitcnt lgkmcnt(4)
	v_mfma_f32_32x32x16_bf16 v[66:81], v[70:73], v[132:135], 0
	v_exp_f32_e32 v178, v178
	v_exp_f32_e32 v179, v179
	v_exp_f32_e32 v162, v162
	v_exp_f32_e32 v163, v163
	s_waitcnt lgkmcnt(3)
	v_mfma_f32_32x32x16_bf16 v[82:97], v[100:103], v[128:131], v[82:97]
	v_add_f32_e32 v148, v178, v148
	v_add_f32_e32 v148, v179, v148
	v_add_f32_e32 v148, v162, v148
	v_exp_f32_e32 v158, v158
	s_waitcnt lgkmcnt(2)
	v_mfma_f32_32x32x16_bf16 v[66:81], v[136:139], v[128:131], v[66:81]
	v_exp_f32_e32 v159, v159
	v_exp_f32_e32 v156, v156
	v_exp_f32_e32 v157, v157
	v_add_f32_e32 v148, v163, v148
	ds_read_b128 v[100:103], v195 offset:49152
	ds_read_b128 v[136:139], v195 offset:57344
	s_waitcnt lgkmcnt(3)
	v_mfma_f32_32x32x16_bf16 v[82:97], v[234:237], v[124:127], v[82:97]
	v_add_f32_e32 v148, v158, v148
	v_add_f32_e32 v148, v159, v148
	v_add_f32_e32 v148, v156, v148
	v_add_f32_e32 v148, v157, v148
	s_waitcnt lgkmcnt(2)
	v_mfma_f32_32x32x16_bf16 v[66:81], v[238:241], v[124:127], v[66:81]
	v_add_f32_e32 v148, v140, v148
	v_add_f32_e32 v148, v141, v148
	v_add_f32_e32 v148, v142, v148
	v_add_f32_e32 v148, v143, v148
	ds_read_b128 v[234:237], v169 offset:49280
	ds_read_b128 v[238:241], v169 offset:57472
	s_waitcnt lgkmcnt(3)
	v_mfma_f32_32x32x16_bf16 v[82:97], v[100:103], v[120:123], v[82:97]
	v_add_f32_e32 v148, v144, v148
	v_add_f32_e32 v148, v145, v148
	v_add_f32_e32 v148, v146, v148
	v_add_f32_e32 v199, v147, v148
	s_waitcnt lgkmcnt(2)
	v_mfma_f32_32x32x16_bf16 v[66:81], v[136:139], v[120:123], v[66:81]
	v_mov_b32_e32 v200, v199
	s_nop 1
	v_permlane32_swap_b32_e32 v199, v200
	v_cvt_pk_bf16_f32 v148, v231, v233
	v_cvt_pk_bf16_f32 v149, v229, v232
	v_cvt_pk_bf16_f32 v150, v228, v230
	ds_read_b128 v[100:103], v193 offset:49280
	ds_read_b128 v[136:139], v193 offset:57472
	s_waitcnt lgkmcnt(3)
	v_mfma_f32_32x32x16_bf16 v[82:97], v[234:237], v[116:119], v[82:97]
	v_cvt_pk_bf16_f32 v151, v226, v227
	v_cvt_pk_bf16_f32 v152, v223, v225
	v_cvt_pk_bf16_f32 v153, v209, v224
	s_waitcnt lgkmcnt(2)
	v_mfma_f32_32x32x16_bf16 v[66:81], v[238:241], v[116:119], v[66:81]
	v_cvt_pk_bf16_f32 v154, v206, v208
	v_cvt_pk_bf16_f32 v155, v205, v207
	v_cvt_pk_bf16_f32 v158, v158, v159
	ds_read_b128 v[234:237], v194 offset:49280
	ds_read_b128 v[238:241], v194 offset:57472
	s_waitcnt lgkmcnt(3)
	v_mfma_f32_32x32x16_bf16 v[82:97], v[100:103], v[112:115], v[82:97]
	v_cvt_pk_bf16_f32 v159, v156, v157
	v_cvt_pk_bf16_f32 v156, v178, v179
	v_cvt_pk_bf16_f32 v157, v162, v163
	s_waitcnt lgkmcnt(2)
	v_mfma_f32_32x32x16_bf16 v[66:81], v[136:139], v[112:115], v[66:81]
	v_cvt_pk_bf16_f32 v160, v140, v141
	v_cvt_pk_bf16_f32 v161, v142, v143
	v_cvt_pk_bf16_f32 v162, v144, v145
	ds_read_b128 v[100:103], v195 offset:49280
	ds_read_b128 v[136:139], v195 offset:57472
	ds_read_b64_tr_b16 v[172:173], v185 offset:0
	ds_read_b64_tr_b16 v[174:175], v185 offset:0x800
	ds_read_b64_tr_b16 v[202:203], v185 offset:0x1000
	ds_read_b64_tr_b16 v[204:205], v185 offset:0x1800
	ds_read_b64_tr_b16 v[206:207], v185 offset:0x2000
	ds_read_b64_tr_b16 v[208:209], v185 offset:0x2800
	ds_read_b64_tr_b16 v[224:225], v185 offset:0x3000
	ds_read_b64_tr_b16 v[226:227], v185 offset:0x3800
	s_waitcnt lgkmcnt(11)
	v_mfma_f32_32x32x16_bf16 v[82:97], v[234:237], v[108:111], v[82:97]
	v_cvt_pk_bf16_f32 v163, v146, v147
	s_nop 0
	v_permlane32_swap_b32_e32 v148, v150
	v_permlane32_swap_b32_e32 v149, v151
	s_waitcnt lgkmcnt(10)
	v_mfma_f32_32x32x16_bf16 v[66:81], v[238:241], v[108:111], v[66:81]
	v_permlane32_swap_b32_e32 v152, v154
	v_permlane32_swap_b32_e32 v153, v155
	v_permlane32_swap_b32_e32 v156, v158
	s_waitcnt lgkmcnt(9)
	v_mfma_f32_32x32x16_bf16 v[82:97], v[100:103], v[104:107], v[82:97]
	v_permlane32_swap_b32_e32 v157, v159
	v_permlane32_swap_b32_e32 v160, v162
	v_permlane32_swap_b32_e32 v161, v163
	s_waitcnt lgkmcnt(8)
	v_mfma_f32_32x32x16_bf16 v[66:81], v[136:139], v[104:107], v[66:81]
	v_add_u32_e32 v169, s100, v169
	v_add_u32_e32 v193, s100, v193
	v_add_u32_e32 v194, s100, v194
	v_add_u32_e32 v195, s100, v195
	s_sub_i32 s100, 0, s100
	s_sub_i32 m0, 0, s100
	s_max_i32 m0, m0, 0
	s_add_i32 m0, m0, s32
	s_add_i32 m0, m0, 0x4000
	s_nop 0
	global_load_lds_dwordx4 v[244:245], off
	s_add_i32 m0, m0, 0x2000
	s_nop 0
	global_load_lds_dwordx4 v[246:247], off
	v_lshl_add_u64 v[244:245], v[244:245], 0, v[250:251]
	v_lshl_add_u64 v[246:247], v[246:247], 0, v[250:251]
	s_sub_i32 m0, 0, s100
	s_max_i32 m0, m0, 0
	s_add_i32 m0, m0, s32
	s_add_i32 m0, m0, s32
	s_sub_i32 m0, m0, 0x10000
	s_nop 0
	global_load_lds_dwordx4 v[248:249], off
	s_add_i32 m0, m0, 896
	s_nop 0
	global_load_lds_dwordx4 v[248:249], off offset:128
	v_lshl_add_u64 v[248:249], v[248:249], 0, v[250:251]
	s_waitcnt lgkmcnt(0)
; __device__ __forceinline__ void mask_tile(f32x16& p0, f32x16& p1, int dq, unsigned W) {
;     const float NEG = -__builtin_inff();
; #pragma unroll
;     for (int r = 0; r < 16; ++r) {
;         const int c = (r & 3) + 8 * (r >> 2);
;         if ((unsigned)(dq - c) >= W) p0[r] = NEG;
;         if ((unsigned)(dq - c - 32) >= W) p1[r] = NEG;
;     }
; }
; template <int VB>
; __device__ __forceinline__ void pv_tile(f32x16* o, int vb0, bf16x8 pa0, bf16x8 pa1, bf16x8 pa2, bf16x8 pa3) {
;     ...
;     PV_D0(0); PV_D0(1); PV_D0(2); PV_D0(3);
;     ...
; }
	s_nop 0
	v_mfma_f32_32x32x16_bf16 v[50:65], v[148:151], v[172:175], v[50:65]
	ds_read_b64_tr_b16 v[172:173], v185 offset:0x200
	ds_read_b64_tr_b16 v[174:175], v185 offset:0xa00
	v_mfma_f32_32x32x16_bf16 v[50:65], v[152:155], v[202:205], v[50:65]
	ds_read_b64_tr_b16 v[202:203], v185 offset:0x1200
	ds_read_b64_tr_b16 v[204:205], v185 offset:0x1a00
	v_mfma_f32_32x32x16_bf16 v[50:65], v[156:159], v[206:209], v[50:65]
	ds_read_b64_tr_b16 v[206:207], v185 offset:0x2200
	ds_read_b64_tr_b16 v[208:209], v185 offset:0x2a00
	v_mfma_f32_32x32x16_bf16 v[50:65], v[160:163], v[224:227], v[50:65]
	ds_read_b64_tr_b16 v[224:225], v185 offset:0x3200
	ds_read_b64_tr_b16 v[226:227], v185 offset:0x3a00
	s_waitcnt lgkmcnt(0)
	v_mfma_f32_32x32x16_bf16 v[34:49], v[148:151], v[172:175], v[34:49]
	ds_read_b64_tr_b16 v[172:173], v185 offset:0x400
	ds_read_b64_tr_b16 v[174:175], v185 offset:0xc00
	v_mfma_f32_32x32x16_bf16 v[34:49], v[152:155], v[202:205], v[34:49]
	ds_read_b64_tr_b16 v[202:203], v185 offset:0x1400
	ds_read_b64_tr_b16 v[204:205], v185 offset:0x1c00
	v_mfma_f32_32x32x16_bf16 v[34:49], v[156:159], v[206:209], v[34:49]
	ds_read_b64_tr_b16 v[206:207], v185 offset:0x2400
	ds_read_b64_tr_b16 v[208:209], v185 offset:0x2c00
	v_mfma_f32_32x32x16_bf16 v[34:49], v[160:163], v[224:227], v[34:49]
	ds_read_b64_tr_b16 v[224:225], v185 offset:0x3400
	ds_read_b64_tr_b16 v[226:227], v185 offset:0x3c00
	s_waitcnt lgkmcnt(0)
	v_mfma_f32_32x32x16_bf16 v[18:33], v[148:151], v[172:175], v[18:33]
	ds_read_b64_tr_b16 v[172:173], v185 offset:0x600
	ds_read_b64_tr_b16 v[174:175], v185 offset:0xe00
	v_mfma_f32_32x32x16_bf16 v[18:33], v[152:155], v[202:205], v[18:33]
	ds_read_b64_tr_b16 v[202:203], v185 offset:0x1600
	ds_read_b64_tr_b16 v[204:205], v185 offset:0x1e00
	v_mfma_f32_32x32x16_bf16 v[18:33], v[156:159], v[206:209], v[18:33]
	ds_read_b64_tr_b16 v[206:207], v185 offset:0x2600
	ds_read_b64_tr_b16 v[208:209], v185 offset:0x2e00
	v_mfma_f32_32x32x16_bf16 v[18:33], v[160:163], v[224:227], v[18:33]
	ds_read_b64_tr_b16 v[224:225], v185 offset:0x3600
	ds_read_b64_tr_b16 v[226:227], v185 offset:0x3e00
	s_waitcnt lgkmcnt(0)
	v_mfma_f32_32x32x16_bf16 v[2:17], v[148:151], v[172:175], v[2:17]
	s_cmp_le_i32 s7, s6
	v_mfma_f32_32x32x16_bf16 v[2:17], v[152:155], v[202:205], v[2:17]
	v_mfma_f32_32x32x16_bf16 v[2:17], v[156:159], v[206:209], v[2:17]
	v_mfma_f32_32x32x16_bf16 v[2:17], v[160:163], v[224:227], v[2:17]
	s_cbranch_scc1 .LBB0_91
	v_add_u32_e32 v148, 0x4000007b, v197
	v_cmp_gt_u32_e32 vcc, 2.0, v148
	v_add_u32_e32 v148, 0x5b, v197
	s_nop 0
	v_cndmask_b32_e32 v82, v220, v82, vcc
	v_cmp_lt_u32_e32 vcc, s33, v148
	v_add_u32_e32 v148, 0x7a, v197
	s_nop 0
	v_cndmask_b32_e32 v66, v220, v66, vcc
	v_cmp_lt_u32_e32 vcc, s33, v148
	v_add_u32_e32 v148, 0x5a, v197
	s_nop 0
	v_cndmask_b32_e32 v83, v220, v83, vcc
	v_cmp_lt_u32_e32 vcc, s33, v148
	v_add_u32_e32 v148, 0x79, v197
	s_nop 0
	v_cndmask_b32_e32 v67, v220, v67, vcc
	v_cmp_lt_u32_e32 vcc, s33, v148
	v_add_u32_e32 v148, 0x59, v197
	s_nop 0
	v_cndmask_b32_e32 v84, v220, v84, vcc
	v_cmp_lt_u32_e32 vcc, s33, v148
	v_add_u32_e32 v148, 0x78, v197
	s_nop 0
	v_cndmask_b32_e32 v68, v220, v68, vcc
	v_cmp_lt_u32_e32 vcc, s33, v148
	v_add_u32_e32 v148, 0x58, v197
	s_nop 0
	v_cndmask_b32_e32 v85, v220, v85, vcc
	v_cmp_lt_u32_e32 vcc, s33, v148
	v_add_u32_e32 v148, 0x73, v197
	s_nop 0
	v_cndmask_b32_e32 v69, v220, v69, vcc
	v_cmp_lt_u32_e32 vcc, s33, v148
	v_add_u32_e32 v148, 0x53, v197
	s_nop 0
	v_cndmask_b32_e32 v86, v220, v86, vcc
	v_cmp_lt_u32_e32 vcc, s33, v148
	v_add_u32_e32 v148, 0x72, v197
	s_nop 0
	v_cndmask_b32_e32 v70, v220, v70, vcc
	v_cmp_lt_u32_e32 vcc, s33, v148
	v_add_u32_e32 v148, 0x52, v197
	s_nop 0
	v_cndmask_b32_e32 v87, v220, v87, vcc
	v_cmp_lt_u32_e32 vcc, s33, v148
	v_add_u32_e32 v148, 0x71, v197
	s_nop 0
	v_cndmask_b32_e32 v71, v220, v71, vcc
	v_cmp_lt_u32_e32 vcc, s33, v148
	v_add_u32_e32 v148, 0x51, v197
	s_nop 0
	v_cndmask_b32_e32 v88, v220, v88, vcc
	v_cmp_lt_u32_e32 vcc, s33, v148
	v_add_u32_e32 v148, 0x70, v197
	s_nop 0
	v_cndmask_b32_e32 v72, v220, v72, vcc
	v_cmp_lt_u32_e32 vcc, s33, v148
	v_add_u32_e32 v148, 0x50, v197
	s_nop 0
	v_cndmask_b32_e32 v89, v220, v89, vcc
	v_cmp_lt_u32_e32 vcc, s33, v148
	v_add_u32_e32 v148, 0x6b, v197
	s_nop 0
	v_cndmask_b32_e32 v73, v220, v73, vcc
	v_cmp_lt_u32_e32 vcc, s33, v148
	v_add_u32_e32 v148, 0x4b, v197
	s_nop 0
	v_cndmask_b32_e32 v90, v220, v90, vcc
	v_cmp_lt_u32_e32 vcc, s33, v148
	v_add_u32_e32 v148, 0x6a, v197
	s_nop 0
	v_cndmask_b32_e32 v74, v220, v74, vcc
	v_cmp_lt_u32_e32 vcc, s33, v148
	v_add_u32_e32 v148, 0x4a, v197
	s_nop 0
	v_cndmask_b32_e32 v91, v220, v91, vcc
	v_cmp_lt_u32_e32 vcc, s33, v148
	v_add_u32_e32 v148, 0x69, v197
	s_nop 0
	v_cndmask_b32_e32 v75, v220, v75, vcc
	v_cmp_lt_u32_e32 vcc, s33, v148
	v_add_u32_e32 v148, 0x49, v197
	s_nop 0
	v_cndmask_b32_e32 v92, v220, v92, vcc
	v_cmp_lt_u32_e32 vcc, s33, v148
	v_add_u32_e32 v148, 0x68, v197
	s_nop 0
	v_cndmask_b32_e32 v76, v220, v76, vcc
	v_cmp_lt_u32_e32 vcc, s33, v148
	v_add_u32_e32 v148, 0x48, v197
	s_nop 0
	v_cndmask_b32_e32 v93, v220, v93, vcc
	v_cmp_lt_u32_e32 vcc, s33, v148
	v_add_u32_e32 v148, 0x63, v197
	s_nop 0
	v_cndmask_b32_e32 v77, v220, v77, vcc
	v_cmp_lt_u32_e32 vcc, s33, v148
	v_add_u32_e32 v148, 0x43, v197
	s_nop 0
	v_cndmask_b32_e32 v94, v220, v94, vcc
	v_cmp_lt_u32_e32 vcc, s33, v148
	v_add_u32_e32 v148, 0x62, v197
	s_nop 0
	v_cndmask_b32_e32 v78, v220, v78, vcc
	v_cmp_lt_u32_e32 vcc, s33, v148
	v_add_u32_e32 v148, 0x42, v197
	s_nop 0
	v_cndmask_b32_e32 v95, v220, v95, vcc
	v_cmp_lt_u32_e32 vcc, s33, v148
	v_add_u32_e32 v148, 0x61, v197
	s_nop 0
	v_cndmask_b32_e32 v79, v220, v79, vcc
	v_cmp_lt_u32_e32 vcc, s33, v148
	v_add_u32_e32 v148, 0x41, v197
	s_nop 0
	v_cndmask_b32_e32 v96, v220, v96, vcc
	v_cmp_lt_u32_e32 vcc, s33, v148
	v_add_u32_e32 v148, 0x60, v197
	s_nop 0
	v_cndmask_b32_e32 v80, v220, v80, vcc
	v_cmp_lt_u32_e32 vcc, s33, v148
	v_add_u32_e32 v148, 64, v197
	s_nop 0
	v_cndmask_b32_e32 v97, v220, v97, vcc
	v_cmp_lt_u32_e32 vcc, s33, v148
	s_nop 1
	v_cndmask_b32_e32 v81, v220, v81, vcc

; __device__ __forceinline__ void partialSM(f32x16& p0, f32x16& p1, float& m_reg, float& mn, float& alpha, bool rs) {
;     ...
;     constexpr float C2 = 1.4426950408889634f * SCALE;
;     if (__builtin_expect(__all((pmax - m_reg) * SCALE <= THR), 1)) { mn = m_reg; alpha = 1.f; }
;     else { mn = fmaxf(m_reg, pmax); alpha = __builtin_amdgcn_exp2f((m_reg - mn) * C2); m_reg = mn; }
;     const float mnL = rs ? -mn * C2 : -__builtin_inff();
;     for (int r = 0; r < 16; ++r) p0[r] = fmaf(p0[r], C2, mnL); for (int r = 0; r < 16; ++r) p1[r] = fmaf(p1[r], C2, mnL);
;     for (int r = 0; r < 16; ++r) p0[r] = __builtin_amdgcn_exp2f(p0[r]);
; }
; template <int KB>
; __device__ __forceinline__ void qkt(f32x16& p0, f32x16& p1, const char* K_lds, int r32, int hi, const bf16x8* qr) {
;     p0 = f32x16{}; p1 = f32x16{};
;     const char* kb[4];
; #pragma unroll
;     for (int dd = 0; dd < 4; ++dd) kb[dd] = K_lds + KB * SHM_K + KSWZ(r32, (dd * 16 + hi * 8) * 2);
; #pragma unroll
;     for (int d0 = 0; d0 < 8; ++d0) { const char* a = kb[d0 & 3] + (d0 >> 2) * 128;
;         bf16x8 b0 = *reinterpret_cast<const bf16x8*>(a);
;         bf16x8 b1 = *reinterpret_cast<const bf16x8*>(a + 32 * 256);
;         p0 = __builtin_amdgcn_mfma_f32_32x32x16_bf16(b0, qr[d0], p0, 0, 0, 0);
;         p1 = __builtin_amdgcn_mfma_f32_32x32x16_bf16(b1, qr[d0], p1, 0, 0, 0); }
; }
.LBB0_95:
	v_cndmask_b32_e64 v179, v148, v198, s[42:43]
	v_mul_f32_e32 v148, 0xbe0293ee, v179
	v_cndmask_b32_e64 v180, v220, v148, s[40:41]
	v_fmamk_f32 v82, v82, 0x3e0293ee, v180
	v_fmamk_f32 v83, v83, 0x3e0293ee, v180
	v_fmamk_f32 v84, v84, 0x3e0293ee, v180
	v_fmamk_f32 v85, v85, 0x3e0293ee, v180
	v_fmamk_f32 v86, v86, 0x3e0293ee, v180
	v_fmamk_f32 v87, v87, 0x3e0293ee, v180
	v_fmamk_f32 v88, v88, 0x3e0293ee, v180
	v_fmamk_f32 v89, v89, 0x3e0293ee, v180
	v_fmamk_f32 v90, v90, 0x3e0293ee, v180
	v_fmamk_f32 v91, v91, 0x3e0293ee, v180
	v_fmamk_f32 v92, v92, 0x3e0293ee, v180
	v_fmamk_f32 v93, v93, 0x3e0293ee, v180
	v_fmamk_f32 v94, v94, 0x3e0293ee, v180
	v_fmamk_f32 v95, v95, 0x3e0293ee, v180
	v_fmamk_f32 v96, v96, 0x3e0293ee, v180
	v_fmamk_f32 v97, v97, 0x3e0293ee, v180
	v_exp_f32_e32 v148, v82
	v_exp_f32_e32 v163, v83
	v_exp_f32_e32 v149, v84
	v_exp_f32_e32 v162, v85
	v_exp_f32_e32 v150, v86
	v_exp_f32_e32 v161, v87
	v_exp_f32_e32 v151, v88
	v_exp_f32_e32 v160, v89
	v_exp_f32_e32 v152, v90
	v_exp_f32_e32 v159, v91
	v_exp_f32_e32 v153, v92
	v_exp_f32_e32 v158, v93
	v_exp_f32_e32 v154, v94
	v_exp_f32_e32 v157, v95
	v_exp_f32_e32 v155, v96
	v_exp_f32_e32 v156, v97
	v_fmamk_f32 v203, v73, 0x3e0293ee, v180
	v_fmamk_f32 v204, v74, 0x3e0293ee, v180
	v_fmamk_f32 v208, v66, 0x3e0293ee, v180
	v_fmamk_f32 v209, v67, 0x3e0293ee, v180
	v_fmamk_f32 v223, v68, 0x3e0293ee, v180
	v_fmamk_f32 v224, v69, 0x3e0293ee, v180
	v_fmamk_f32 v225, v70, 0x3e0293ee, v180
	v_fmamk_f32 v198, v71, 0x3e0293ee, v180
	v_fmamk_f32 v201, v72, 0x3e0293ee, v180
	v_fmamk_f32 v205, v75, 0x3e0293ee, v180
	v_fmamk_f32 v206, v76, 0x3e0293ee, v180
	v_fmamk_f32 v207, v77, 0x3e0293ee, v180
	v_fmamk_f32 v181, v78, 0x3e0293ee, v180
	v_fmamk_f32 v226, v79, 0x3e0293ee, v180
	v_fmamk_f32 v227, v80, 0x3e0293ee, v180
	v_fmac_f32_e32 v180, 0x3e0293ee, v81
	s_waitcnt lgkmcnt(0)
	ds_read_b128 v[66:69], v169 offset:32768
	ds_read_b128 v[70:73], v169 offset:40960
	ds_read_b128 v[172:175], v193 offset:32768
	ds_read_b128 v[228:231], v193 offset:40960
	ds_read_b128 v[234:237], v194 offset:32768
	ds_read_b128 v[238:241], v194 offset:40960
	v_exp_f32_e32 v198, v198
	v_exp_f32_e32 v201, v201
	v_exp_f32_e32 v214, v204
	v_exp_f32_e32 v205, v205
	v_exp_f32_e32 v206, v206
	v_exp_f32_e32 v207, v207
	v_exp_f32_e32 v181, v181
	v_exp_f32_e32 v215, v226
	v_exp_f32_e32 v216, v227
	v_exp_f32_e32 v180, v180
	v_exp_f32_e32 v218, v209
	v_exp_f32_e32 v209, v203
	v_add_f32_e32 v203, 0, v148
	v_add_f32_e32 v203, v163, v203
	v_add_f32_e32 v203, v149, v203
	v_add_f32_e32 v203, v162, v203
	v_add_f32_e32 v203, v150, v203
	v_add_f32_e32 v203, v161, v203
	v_add_f32_e32 v203, v151, v203
	v_add_f32_e32 v203, v160, v203
	s_waitcnt lgkmcnt(5)
	v_mfma_f32_32x32x16_bf16 v[82:97], v[66:69], v[132:135], 0
	v_add_f32_e32 v203, v152, v203
	v_add_f32_e32 v203, v159, v203
	v_add_f32_e32 v203, v153, v203
	v_add_f32_e32 v203, v158, v203
	s_waitcnt lgkmcnt(4)
	v_mfma_f32_32x32x16_bf16 v[66:81], v[70:73], v[132:135], 0
	v_exp_f32_e32 v217, v208
	v_add_f32_e32 v203, v154, v203
	v_add_f32_e32 v203, v157, v203
	v_exp_f32_e32 v219, v223
	s_waitcnt lgkmcnt(3)
	v_mfma_f32_32x32x16_bf16 v[82:97], v[172:175], v[128:131], v[82:97]
	v_add_f32_e32 v203, v155, v203
	v_exp_f32_e32 v222, v224
	v_add_f32_e32 v203, v156, v203
	v_exp_f32_e32 v208, v225
	s_waitcnt lgkmcnt(2)
	v_mfma_f32_32x32x16_bf16 v[66:81], v[228:231], v[128:131], v[66:81]
	v_add_f32_e32 v203, v217, v203
	v_add_f32_e32 v203, v218, v203
	v_add_f32_e32 v203, v219, v203
	v_add_f32_e32 v203, v222, v203
	ds_read_b128 v[172:175], v195 offset:32768
	ds_read_b128 v[228:231], v195 offset:40960
	s_waitcnt lgkmcnt(3)
	v_mfma_f32_32x32x16_bf16 v[82:97], v[234:237], v[124:127], v[82:97]
	v_add_f32_e32 v203, v208, v203
	v_add_f32_e32 v203, v198, v203
	v_add_f32_e32 v203, v201, v203
	v_add_f32_e32 v203, v209, v203
	s_waitcnt lgkmcnt(2)
; __device__ __forceinline__ void finishSM(f32x16& p0, f32x16& p1, float alpha, float& l_reg, bf16x8& pa0, bf16x8& pa1, bf16x8& pa2, bf16x8& pa3) {
;     for (int r = 0; r < 16; ++r) p1[r] = __builtin_amdgcn_exp2f(p1[r]);
;     float ps = 0; for (int r = 0; r < 16; ++r) ps += p0[r]; for (int r = 0; r < 16; ++r) ps += p1[r];
;     { auto rr = __builtin_amdgcn_permlane32_swap(__float_as_uint(ps), __float_as_uint(ps), false, false);
;       ps = __uint_as_float(rr[0]) + __uint_as_float(rr[1]); }
;     l_reg = l_reg * alpha + ps;
;     ...
;     PK4(p0, 0, pa0); PK4(p0, 8, pa1); PK4(p1, 0, pa2); PK4(p1, 8, pa3);
;     ...
; }
; template <int KB>
; __device__ __forceinline__ void qkt(f32x16& p0, f32x16& p1, const char* K_lds, int r32, int hi, const bf16x8* qr) {
;     p0 = f32x16{}; p1 = f32x16{};
;     const char* kb[4];
; #pragma unroll
;     for (int dd = 0; dd < 4; ++dd) kb[dd] = K_lds + KB * SHM_K + KSWZ(r32, (dd * 16 + hi * 8) * 2);
; #pragma unroll
;     for (int d0 = 0; d0 < 8; ++d0) { const char* a = kb[d0 & 3] + (d0 >> 2) * 128;
;         bf16x8 b0 = *reinterpret_cast<const bf16x8*>(a);
;         bf16x8 b1 = *reinterpret_cast<const bf16x8*>(a + 32 * 256);
;         p0 = __builtin_amdgcn_mfma_f32_32x32x16_bf16(b0, qr[d0], p0, 0, 0, 0);
;         p1 = __builtin_amdgcn_mfma_f32_32x32x16_bf16(b1, qr[d0], p1, 0, 0, 0); }
; }
	v_mfma_f32_32x32x16_bf16 v[66:81], v[238:241], v[124:127], v[66:81]
	v_add_f32_e32 v203, v214, v203
	v_add_f32_e32 v203, v205, v203
	v_add_f32_e32 v203, v206, v203
	v_add_f32_e32 v203, v207, v203
	ds_read_b128 v[234:237], v169 offset:32896
	ds_read_b128 v[238:241], v169 offset:41088
	s_waitcnt lgkmcnt(3)
	v_mfma_f32_32x32x16_bf16 v[82:97], v[172:175], v[120:123], v[82:97]
	v_add_f32_e32 v203, v181, v203
	v_add_f32_e32 v203, v215, v203
	v_add_f32_e32 v203, v216, v203
	v_add_f32_e32 v203, v180, v203
	s_waitcnt lgkmcnt(2)
	v_mfma_f32_32x32x16_bf16 v[66:81], v[228:231], v[120:123], v[66:81]
	v_mov_b32_e32 v204, v203
	v_cvt_pk_bf16_f32 v148, v148, v163
	v_cvt_pk_bf16_f32 v149, v149, v162
	v_cvt_pk_bf16_f32 v150, v150, v161
	ds_read_b128 v[172:175], v193 offset:32896
	ds_read_b128 v[228:231], v193 offset:41088
	s_waitcnt lgkmcnt(3)
	v_mfma_f32_32x32x16_bf16 v[82:97], v[234:237], v[116:119], v[82:97]
	v_cvt_pk_bf16_f32 v151, v151, v160
	v_cvt_pk_bf16_f32 v152, v152, v159
	v_cvt_pk_bf16_f32 v153, v153, v158
	v_cvt_pk_bf16_f32 v154, v154, v157
	s_waitcnt lgkmcnt(2)
	v_mfma_f32_32x32x16_bf16 v[66:81], v[238:241], v[116:119], v[66:81]
	v_cvt_pk_bf16_f32 v155, v155, v156
	v_cvt_pk_bf16_f32 v156, v217, v218
	v_cvt_pk_bf16_f32 v157, v219, v222
	ds_read_b128 v[234:237], v194 offset:32896
	ds_read_b128 v[238:241], v194 offset:41088
	s_waitcnt lgkmcnt(3)
	v_mfma_f32_32x32x16_bf16 v[82:97], v[172:175], v[112:115], v[82:97]
	v_cvt_pk_bf16_f32 v158, v208, v198
	v_cvt_pk_bf16_f32 v159, v201, v209
	v_cvt_pk_bf16_f32 v160, v214, v205
	s_waitcnt lgkmcnt(2)
	v_mfma_f32_32x32x16_bf16 v[66:81], v[228:231], v[112:115], v[66:81]
	v_cvt_pk_bf16_f32 v161, v206, v207
	v_cvt_pk_bf16_f32 v162, v181, v215
	v_cvt_pk_bf16_f32 v163, v216, v180
	ds_read_b128 v[172:175], v195 offset:32896
	ds_read_b128 v[228:231], v195 offset:41088
	ds_read_b64_tr_b16 v[206:207], v185 offset:0x5000
	ds_read_b64_tr_b16 v[208:209], v185 offset:0x5800
	ds_read_b64_tr_b16 v[224:225], v185 offset:0x6000
	ds_read_b64_tr_b16 v[226:227], v185 offset:0x6800
	s_waitcnt lgkmcnt(7)
	v_mfma_f32_32x32x16_bf16 v[82:97], v[234:237], v[108:111], v[82:97]
	s_nop 1
	v_permlane32_swap_b32_e32 v203, v204
	v_permlane32_swap_b32_e32 v148, v150
	v_permlane32_swap_b32_e32 v149, v151
	s_waitcnt lgkmcnt(6)
	v_mfma_f32_32x32x16_bf16 v[66:81], v[238:241], v[108:111], v[66:81]
	v_permlane32_swap_b32_e32 v152, v154
	v_permlane32_swap_b32_e32 v153, v155
	v_permlane32_swap_b32_e32 v156, v158
	s_waitcnt lgkmcnt(5)
	v_mfma_f32_32x32x16_bf16 v[82:97], v[172:175], v[104:107], v[82:97]
	v_permlane32_swap_b32_e32 v157, v159
	v_permlane32_swap_b32_e32 v160, v162
	v_permlane32_swap_b32_e32 v161, v163
	s_waitcnt lgkmcnt(4)
	v_mfma_f32_32x32x16_bf16 v[66:81], v[228:231], v[104:107], v[66:81]
	ds_read_b64_tr_b16 v[172:173], v185 offset:0x4000
	ds_read_b64_tr_b16 v[174:175], v185 offset:0x4800
	ds_read_b64_tr_b16 v[228:229], v185 offset:0x7000
	ds_read_b64_tr_b16 v[230:231], v185 offset:0x7800
	s_cmp_lt_u32 s3, s2
	s_cselect_b64 s[22:23], -1, 0
	s_cmp_ge_u32 s3, s2
	s_sub_i32 m0, 0, s100
	s_max_i32 m0, m0, 0
	s_add_i32 m0, m0, s32
	s_add_i32 m0, m0, s32
	s_sub_i32 m0, m0, 0xc000
	s_nop 0
	global_load_lds_dwordx4 v[248:249], off
	s_add_i32 m0, m0, 896
	s_nop 0
	global_load_lds_dwordx4 v[248:249], off offset:128
	v_lshl_add_u64 v[248:249], v[248:249], 0, v[250:251]
	s_add_i32 m0, s3, 1
	s_cmp_ge_u32 m0, s2
	s_cbranch_scc1 .LBB0_97
	s_max_i32 m0, s100, 0
	s_add_i32 m0, m0, s32
	s_nop 0
	global_load_lds_dwordx4 v[244:245], off
	s_add_i32 m0, m0, 0x2000
	s_nop 0
	global_load_lds_dwordx4 v[246:247], off
	v_lshl_add_u64 v[244:245], v[244:245], 0, v[250:251]
	v_lshl_add_u64 v[246:247], v[246:247], 0, v[250:251]
